# v025 + P8->P9 workgroup-local barrier (P9 tasks on own q tiles) + P10 expert scale loads hoisted behind the per-token sort
# baseline (speedup 1.0000x reference)
; __global__ void __launch_bounds__(NT, 2) mk_fwd(Args args) {
;     ...
;         for (int tok = gw; tok < MTOK; tok += NGW) {
;             const int b = tok >> 11;
;             f32x2 hf2[16];
; #pragma unroll
;             for (int j = 0; j < 4; ++j) { const u32x4 a = *(const u32x4*)(HB + (size_t)tok * DM + lane * 32 + j * 8);
;     ...
;             const int e0 = EIDX[(size_t)tok * 128 + lane], e1 = EIDX[(size_t)tok * 128 + 64 + lane];
;             const float g0 = GATE[(size_t)tok * 128 + lane], g1 = GATE[(size_t)tok * 128 + 64 + lane];
.LBB0_886:
	s_ashr_i32 s71, s70, 31
	s_lshl_b64 s[4:5], s[70:71], 9
	v_lshl_or_b32 v0, v128, 2, s4
	v_mov_b32_e32 v1, s5
	v_lshl_add_u64 v[2:3], s[46:47], 0, v[0:1]
	global_load_dword v108, v[2:3], off
	s_lshl_b64 s[4:5], s[70:71], 12
	v_lshl_add_u64 v[2:3], v[96:97], 0, s[4:5]
	global_load_dwordx4 v[32:35], v[2:3], off offset:48
	global_load_dwordx4 v[36:39], v[2:3], off offset:32
	global_load_dwordx4 v[40:43], v[2:3], off offset:16
	global_load_dwordx4 v[44:47], v[2:3], off
	v_or_b32_e32 v2, 0x100, v0
	v_mov_b32_e32 v3, v1
	v_lshl_add_u64 v[0:1], s[48:49], 0, v[0:1]
	v_lshl_add_u64 v[4:5], s[46:47], 0, v[2:3]
	v_lshl_add_u64 v[2:3], s[48:49], 0, v[2:3]
	global_load_dword v106, v[4:5], off
	global_load_dword v110, v[0:1], off
	global_load_dword v156, v[2:3], off
	s_waitcnt vmcnt(0)
	v_lshl_or_b32 v170, v108, 7, v128
	v_lshlrev_b32_e32 v171, 7, v106
	v_or_b32_e32 v174, 64, v128
	v_or_b32_e32 v171, v171, v174
	s_nop 0
	s_xnor_b64 s[62:63], s[50:51], s[52:53]
	s_nop 1
	v_min_u32_dpp v172, v170, v170 quad_perm:[1,0,3,2] row_mask:0xf bank_mask:0xf
	v_max_u32_dpp v173, v170, v170 quad_perm:[1,0,3,2] row_mask:0xf bank_mask:0xf
	v_min_u32_dpp v175, v171, v171 quad_perm:[1,0,3,2] row_mask:0xf bank_mask:0xf
	v_max_u32_dpp v176, v171, v171 quad_perm:[1,0,3,2] row_mask:0xf bank_mask:0xf
	v_cndmask_b32_e64 v170, v173, v172, s[62:63]
	v_cndmask_b32_e64 v171, v176, v175, s[62:63]
	s_xnor_b64 s[62:63], s[52:53], s[54:55]
	s_nop 1
	v_min_u32_dpp v172, v170, v170 quad_perm:[2,3,0,1] row_mask:0xf bank_mask:0xf
	v_max_u32_dpp v173, v170, v170 quad_perm:[2,3,0,1] row_mask:0xf bank_mask:0xf
	v_min_u32_dpp v175, v171, v171 quad_perm:[2,3,0,1] row_mask:0xf bank_mask:0xf
	v_max_u32_dpp v176, v171, v171 quad_perm:[2,3,0,1] row_mask:0xf bank_mask:0xf
	v_cndmask_b32_e64 v170, v173, v172, s[62:63]
	v_cndmask_b32_e64 v171, v176, v175, s[62:63]
	s_xnor_b64 s[62:63], s[50:51], s[54:55]
	s_nop 1
	v_min_u32_dpp v172, v170, v170 quad_perm:[1,0,3,2] row_mask:0xf bank_mask:0xf
	v_max_u32_dpp v173, v170, v170 quad_perm:[1,0,3,2] row_mask:0xf bank_mask:0xf
	v_min_u32_dpp v175, v171, v171 quad_perm:[1,0,3,2] row_mask:0xf bank_mask:0xf
	v_max_u32_dpp v176, v171, v171 quad_perm:[1,0,3,2] row_mask:0xf bank_mask:0xf
	v_cndmask_b32_e64 v170, v173, v172, s[62:63]
	v_cndmask_b32_e64 v171, v176, v175, s[62:63]
	s_xnor_b64 s[62:63], s[54:55], s[56:57]
	s_nop 1
	v_mov_b32_dpp v174, v170 row_half_mirror row_mask:0xf bank_mask:0xf
	v_mov_b32_dpp v177, v171 row_half_mirror row_mask:0xf bank_mask:0xf
	s_nop 0
	v_min_u32_dpp v172, v174, v170 quad_perm:[3,2,1,0] row_mask:0xf bank_mask:0xf
	v_max_u32_dpp v173, v174, v170 quad_perm:[3,2,1,0] row_mask:0xf bank_mask:0xf
	v_min_u32_dpp v175, v177, v171 quad_perm:[3,2,1,0] row_mask:0xf bank_mask:0xf
	v_max_u32_dpp v176, v177, v171 quad_perm:[3,2,1,0] row_mask:0xf bank_mask:0xf
	v_cndmask_b32_e64 v170, v173, v172, s[62:63]
	v_cndmask_b32_e64 v171, v176, v175, s[62:63]
	s_xnor_b64 s[62:63], s[52:53], s[56:57]
	s_nop 1
	v_min_u32_dpp v172, v170, v170 quad_perm:[2,3,0,1] row_mask:0xf bank_mask:0xf
	v_max_u32_dpp v173, v170, v170 quad_perm:[2,3,0,1] row_mask:0xf bank_mask:0xf
	v_min_u32_dpp v175, v171, v171 quad_perm:[2,3,0,1] row_mask:0xf bank_mask:0xf
	v_max_u32_dpp v176, v171, v171 quad_perm:[2,3,0,1] row_mask:0xf bank_mask:0xf
	v_cndmask_b32_e64 v170, v173, v172, s[62:63]
	v_cndmask_b32_e64 v171, v176, v175, s[62:63]
	s_xnor_b64 s[62:63], s[50:51], s[56:57]
	s_nop 1
	v_min_u32_dpp v172, v170, v170 quad_perm:[1,0,3,2] row_mask:0xf bank_mask:0xf
	v_max_u32_dpp v173, v170, v170 quad_perm:[1,0,3,2] row_mask:0xf bank_mask:0xf
	v_min_u32_dpp v175, v171, v171 quad_perm:[1,0,3,2] row_mask:0xf bank_mask:0xf
	v_max_u32_dpp v176, v171, v171 quad_perm:[1,0,3,2] row_mask:0xf bank_mask:0xf
	v_cndmask_b32_e64 v170, v173, v172, s[62:63]
	v_cndmask_b32_e64 v171, v176, v175, s[62:63]
	s_xnor_b64 s[62:63], s[56:57], s[58:59]
	s_nop 1
	v_min_u32_dpp v172, v170, v170 row_ror:8 row_mask:0xf bank_mask:0xf
	v_max_u32_dpp v173, v170, v170 row_ror:8 row_mask:0xf bank_mask:0xf
	v_min_u32_dpp v175, v171, v171 row_ror:8 row_mask:0xf bank_mask:0xf
	v_max_u32_dpp v176, v171, v171 row_ror:8 row_mask:0xf bank_mask:0xf
	v_cndmask_b32_e64 v170, v173, v172, s[62:63]
	v_cndmask_b32_e64 v171, v176, v175, s[62:63]
	s_xnor_b64 s[62:63], s[54:55], s[58:59]
	s_nop 1
	v_mov_b32_dpp v174, v170 row_half_mirror row_mask:0xf bank_mask:0xf
	v_mov_b32_dpp v177, v171 row_half_mirror row_mask:0xf bank_mask:0xf
	s_nop 0
	v_min_u32_dpp v172, v174, v170 quad_perm:[3,2,1,0] row_mask:0xf bank_mask:0xf
	v_max_u32_dpp v173, v174, v170 quad_perm:[3,2,1,0] row_mask:0xf bank_mask:0xf
	v_min_u32_dpp v175, v177, v171 quad_perm:[3,2,1,0] row_mask:0xf bank_mask:0xf
	v_max_u32_dpp v176, v177, v171 quad_perm:[3,2,1,0] row_mask:0xf bank_mask:0xf
	v_cndmask_b32_e64 v170, v173, v172, s[62:63]
	v_cndmask_b32_e64 v171, v176, v175, s[62:63]
	s_xnor_b64 s[62:63], s[52:53], s[58:59]
	s_nop 1
	v_min_u32_dpp v172, v170, v170 quad_perm:[2,3,0,1] row_mask:0xf bank_mask:0xf
	v_max_u32_dpp v173, v170, v170 quad_perm:[2,3,0,1] row_mask:0xf bank_mask:0xf
	v_min_u32_dpp v175, v171, v171 quad_perm:[2,3,0,1] row_mask:0xf bank_mask:0xf
	v_max_u32_dpp v176, v171, v171 quad_perm:[2,3,0,1] row_mask:0xf bank_mask:0xf
	v_cndmask_b32_e64 v170, v173, v172, s[62:63]
	v_cndmask_b32_e64 v171, v176, v175, s[62:63]
	s_xnor_b64 s[62:63], s[50:51], s[58:59]
	s_nop 1
	v_min_u32_dpp v172, v170, v170 quad_perm:[1,0,3,2] row_mask:0xf bank_mask:0xf
	v_max_u32_dpp v173, v170, v170 quad_perm:[1,0,3,2] row_mask:0xf bank_mask:0xf
	v_min_u32_dpp v175, v171, v171 quad_perm:[1,0,3,2] row_mask:0xf bank_mask:0xf
	v_max_u32_dpp v176, v171, v171 quad_perm:[1,0,3,2] row_mask:0xf bank_mask:0xf
	v_cndmask_b32_e64 v170, v173, v172, s[62:63]
	v_cndmask_b32_e64 v171, v176, v175, s[62:63]
	s_xnor_b64 s[62:63], s[58:59], s[60:61]
	ds_bpermute_b32 v174, v146, v170
	ds_bpermute_b32 v177, v146, v171
	s_waitcnt lgkmcnt(1)
; __global__ void __launch_bounds__(NT, 2) mk_fwd(Args args) {
;     ...
;             const int e0 = EIDX[(size_t)tok * 128 + lane], e1 = EIDX[(size_t)tok * 128 + 64 + lane];
;             const float g0 = GATE[(size_t)tok * 128 + lane], g1 = GATE[(size_t)tok * 128 + 64 + lane];
	v_min_u32_e32 v172, v174, v170
	v_max_u32_e32 v173, v174, v170
	s_waitcnt lgkmcnt(0)
	v_min_u32_e32 v175, v177, v171
	v_max_u32_e32 v176, v177, v171
	v_cndmask_b32_e64 v170, v173, v172, s[62:63]
	v_cndmask_b32_e64 v171, v176, v175, s[62:63]
	s_xnor_b64 s[62:63], s[56:57], s[60:61]
	s_nop 1
	v_min_u32_dpp v172, v170, v170 row_ror:8 row_mask:0xf bank_mask:0xf
	v_max_u32_dpp v173, v170, v170 row_ror:8 row_mask:0xf bank_mask:0xf
	v_min_u32_dpp v175, v171, v171 row_ror:8 row_mask:0xf bank_mask:0xf
	v_max_u32_dpp v176, v171, v171 row_ror:8 row_mask:0xf bank_mask:0xf
	v_cndmask_b32_e64 v170, v173, v172, s[62:63]
	v_cndmask_b32_e64 v171, v176, v175, s[62:63]
	s_xnor_b64 s[62:63], s[54:55], s[60:61]
	s_nop 1
	v_mov_b32_dpp v174, v170 row_half_mirror row_mask:0xf bank_mask:0xf
	v_mov_b32_dpp v177, v171 row_half_mirror row_mask:0xf bank_mask:0xf
	s_nop 0
	v_min_u32_dpp v172, v174, v170 quad_perm:[3,2,1,0] row_mask:0xf bank_mask:0xf
	v_max_u32_dpp v173, v174, v170 quad_perm:[3,2,1,0] row_mask:0xf bank_mask:0xf
	v_min_u32_dpp v175, v177, v171 quad_perm:[3,2,1,0] row_mask:0xf bank_mask:0xf
	v_max_u32_dpp v176, v177, v171 quad_perm:[3,2,1,0] row_mask:0xf bank_mask:0xf
	v_cndmask_b32_e64 v170, v173, v172, s[62:63]
	v_cndmask_b32_e64 v171, v176, v175, s[62:63]
	s_xnor_b64 s[62:63], s[52:53], s[60:61]
	s_nop 1
	v_min_u32_dpp v172, v170, v170 quad_perm:[2,3,0,1] row_mask:0xf bank_mask:0xf
	v_max_u32_dpp v173, v170, v170 quad_perm:[2,3,0,1] row_mask:0xf bank_mask:0xf
	v_min_u32_dpp v175, v171, v171 quad_perm:[2,3,0,1] row_mask:0xf bank_mask:0xf
	v_max_u32_dpp v176, v171, v171 quad_perm:[2,3,0,1] row_mask:0xf bank_mask:0xf
	v_cndmask_b32_e64 v170, v173, v172, s[62:63]
	v_cndmask_b32_e64 v171, v176, v175, s[62:63]
	s_xnor_b64 s[62:63], s[50:51], s[60:61]
	s_nop 1
	v_min_u32_dpp v172, v170, v170 quad_perm:[1,0,3,2] row_mask:0xf bank_mask:0xf
	v_max_u32_dpp v173, v170, v170 quad_perm:[1,0,3,2] row_mask:0xf bank_mask:0xf
	v_min_u32_dpp v175, v171, v171 quad_perm:[1,0,3,2] row_mask:0xf bank_mask:0xf
	v_max_u32_dpp v176, v171, v171 quad_perm:[1,0,3,2] row_mask:0xf bank_mask:0xf
	v_cndmask_b32_e64 v170, v173, v172, s[62:63]
	v_cndmask_b32_e64 v171, v176, v175, s[62:63]
	ds_bpermute_b32 v174, v129, v170
	ds_bpermute_b32 v177, v129, v171
	s_waitcnt lgkmcnt(1)
	v_min_u32_e32 v172, v174, v170
	v_max_u32_e32 v173, v174, v170
	s_waitcnt lgkmcnt(0)
	v_min_u32_e32 v175, v177, v171
	v_max_u32_e32 v176, v177, v171
	v_cndmask_b32_e64 v170, v173, v172, s[60:61]
	v_cndmask_b32_e64 v171, v175, v176, s[60:61]
	ds_bpermute_b32 v174, v146, v170
	ds_bpermute_b32 v177, v146, v171
	s_waitcnt lgkmcnt(1)
	v_min_u32_e32 v172, v174, v170
	v_max_u32_e32 v173, v174, v170
	s_waitcnt lgkmcnt(0)
	v_min_u32_e32 v175, v177, v171
	v_max_u32_e32 v176, v177, v171
	v_cndmask_b32_e64 v170, v173, v172, s[58:59]
	v_cndmask_b32_e64 v171, v175, v176, s[58:59]
	s_nop 1
	v_min_u32_dpp v172, v170, v170 row_ror:8 row_mask:0xf bank_mask:0xf
	v_max_u32_dpp v173, v170, v170 row_ror:8 row_mask:0xf bank_mask:0xf
	v_min_u32_dpp v175, v171, v171 row_ror:8 row_mask:0xf bank_mask:0xf
	v_max_u32_dpp v176, v171, v171 row_ror:8 row_mask:0xf bank_mask:0xf
	v_cndmask_b32_e64 v170, v173, v172, s[56:57]
	v_cndmask_b32_e64 v171, v175, v176, s[56:57]
	s_nop 1
	v_mov_b32_dpp v174, v170 row_half_mirror row_mask:0xf bank_mask:0xf
	v_mov_b32_dpp v177, v171 row_half_mirror row_mask:0xf bank_mask:0xf
	s_nop 0
	v_min_u32_dpp v172, v174, v170 quad_perm:[3,2,1,0] row_mask:0xf bank_mask:0xf
	v_max_u32_dpp v173, v174, v170 quad_perm:[3,2,1,0] row_mask:0xf bank_mask:0xf
	v_min_u32_dpp v175, v177, v171 quad_perm:[3,2,1,0] row_mask:0xf bank_mask:0xf
	v_max_u32_dpp v176, v177, v171 quad_perm:[3,2,1,0] row_mask:0xf bank_mask:0xf
	v_cndmask_b32_e64 v170, v173, v172, s[54:55]
	v_cndmask_b32_e64 v171, v175, v176, s[54:55]
	s_nop 1
	v_min_u32_dpp v172, v170, v170 quad_perm:[2,3,0,1] row_mask:0xf bank_mask:0xf
	v_max_u32_dpp v173, v170, v170 quad_perm:[2,3,0,1] row_mask:0xf bank_mask:0xf
	v_min_u32_dpp v175, v171, v171 quad_perm:[2,3,0,1] row_mask:0xf bank_mask:0xf
	v_max_u32_dpp v176, v171, v171 quad_perm:[2,3,0,1] row_mask:0xf bank_mask:0xf
	v_cndmask_b32_e64 v170, v173, v172, s[52:53]
	v_cndmask_b32_e64 v171, v175, v176, s[52:53]
	s_nop 1
	v_min_u32_dpp v172, v170, v170 quad_perm:[1,0,3,2] row_mask:0xf bank_mask:0xf
	v_max_u32_dpp v173, v170, v170 quad_perm:[1,0,3,2] row_mask:0xf bank_mask:0xf
	v_min_u32_dpp v175, v171, v171 quad_perm:[1,0,3,2] row_mask:0xf bank_mask:0xf
	v_max_u32_dpp v176, v171, v171 quad_perm:[1,0,3,2] row_mask:0xf bank_mask:0xf
	v_cndmask_b32_e64 v170, v173, v172, s[50:51]
	v_cndmask_b32_e64 v171, v175, v176, s[50:51]
	v_min_u32_e32 v172, v170, v171
	v_max_u32_e32 v171, v170, v171
	v_mov_b32_e32 v170, v172
	ds_bpermute_b32 v174, v129, v170
	ds_bpermute_b32 v177, v129, v171
	s_waitcnt lgkmcnt(1)
	v_min_u32_e32 v172, v174, v170
	v_max_u32_e32 v173, v174, v170
	s_waitcnt lgkmcnt(0)
	v_min_u32_e32 v175, v177, v171
	v_max_u32_e32 v176, v177, v171
	v_cndmask_b32_e64 v170, v173, v172, s[60:61]
	v_cndmask_b32_e64 v171, v176, v175, s[60:61]
	ds_bpermute_b32 v174, v146, v170
	ds_bpermute_b32 v177, v146, v171
	s_waitcnt lgkmcnt(1)
	v_min_u32_e32 v172, v174, v170
	v_max_u32_e32 v173, v174, v170
	s_waitcnt lgkmcnt(0)
; #define PU_LOAD(BUF, EV, S0) do { _Pragma("unroll") for (int i = 0; i < 8; ++i) { const int row_ = __builtin_amdgcn_readlane(EV, (S0) + i); BUF[i & 3][i >> 2] = *(const u32x4*)(PU8 + (size_t)row_ * 1024 + lane * 16); } } while (0)
; __global__ void __launch_bounds__(NT, 2) mk_fwd(Args args) {
;     ...
;             const int e0 = EIDX[(size_t)tok * 128 + lane], e1 = EIDX[(size_t)tok * 128 + 64 + lane];
;             const float g0 = GATE[(size_t)tok * 128 + lane], g1 = GATE[(size_t)tok * 128 + 64 + lane];
;             const bool hi32 = (lane & 32) != 0, hi16 = (lane & 16) != 0; const int l3 = (lane & 3) << 4;
;     ...
;             float act0 = 0.f, act1 = 0.f;
;             u32x4 bA[4][2], bB[4][2];
; #pragma unroll
;             for (int hh = 0; hh < 2; ++hh) {
;                 const int ev = hh ? e1 : e0; const float gv = hh ? g1 : g0; float dv = 0.f;
;                 PU_LOAD(bA, ev, 0);
	v_min_u32_e32 v175, v177, v171
	v_max_u32_e32 v176, v177, v171
	v_cndmask_b32_e64 v170, v173, v172, s[58:59]
	v_cndmask_b32_e64 v171, v176, v175, s[58:59]
	s_nop 1
	v_min_u32_dpp v172, v170, v170 row_ror:8 row_mask:0xf bank_mask:0xf
	v_max_u32_dpp v173, v170, v170 row_ror:8 row_mask:0xf bank_mask:0xf
	v_min_u32_dpp v175, v171, v171 row_ror:8 row_mask:0xf bank_mask:0xf
	v_max_u32_dpp v176, v171, v171 row_ror:8 row_mask:0xf bank_mask:0xf
	v_cndmask_b32_e64 v170, v173, v172, s[56:57]
	v_cndmask_b32_e64 v171, v176, v175, s[56:57]
	s_nop 1
	v_mov_b32_dpp v174, v170 row_half_mirror row_mask:0xf bank_mask:0xf
	v_mov_b32_dpp v177, v171 row_half_mirror row_mask:0xf bank_mask:0xf
	s_nop 0
	v_min_u32_dpp v172, v174, v170 quad_perm:[3,2,1,0] row_mask:0xf bank_mask:0xf
	v_max_u32_dpp v173, v174, v170 quad_perm:[3,2,1,0] row_mask:0xf bank_mask:0xf
	v_min_u32_dpp v175, v177, v171 quad_perm:[3,2,1,0] row_mask:0xf bank_mask:0xf
	v_max_u32_dpp v176, v177, v171 quad_perm:[3,2,1,0] row_mask:0xf bank_mask:0xf
	v_cndmask_b32_e64 v170, v173, v172, s[54:55]
	v_cndmask_b32_e64 v171, v176, v175, s[54:55]
	s_nop 1
	v_min_u32_dpp v172, v170, v170 quad_perm:[2,3,0,1] row_mask:0xf bank_mask:0xf
	v_max_u32_dpp v173, v170, v170 quad_perm:[2,3,0,1] row_mask:0xf bank_mask:0xf
	v_min_u32_dpp v175, v171, v171 quad_perm:[2,3,0,1] row_mask:0xf bank_mask:0xf
	v_max_u32_dpp v176, v171, v171 quad_perm:[2,3,0,1] row_mask:0xf bank_mask:0xf
	v_cndmask_b32_e64 v170, v173, v172, s[52:53]
	v_cndmask_b32_e64 v171, v176, v175, s[52:53]
	s_nop 1
	v_min_u32_dpp v172, v170, v170 quad_perm:[1,0,3,2] row_mask:0xf bank_mask:0xf
	v_max_u32_dpp v173, v170, v170 quad_perm:[1,0,3,2] row_mask:0xf bank_mask:0xf
	v_min_u32_dpp v175, v171, v171 quad_perm:[1,0,3,2] row_mask:0xf bank_mask:0xf
	v_max_u32_dpp v176, v171, v171 quad_perm:[1,0,3,2] row_mask:0xf bank_mask:0xf
	v_cndmask_b32_e64 v170, v173, v172, s[50:51]
	v_cndmask_b32_e64 v171, v176, v175, s[50:51]
	v_and_b32_e32 v172, 63, v170
	v_lshlrev_b32_e32 v172, 2, v172
	ds_bpermute_b32 v173, v172, v110
	ds_bpermute_b32 v174, v172, v156
	v_and_b32_e32 v175, 63, v171
	v_lshlrev_b32_e32 v175, 2, v175
	ds_bpermute_b32 v176, v175, v110
	ds_bpermute_b32 v177, v175, v156
	v_and_b32_e32 v172, 64, v170
	v_cmp_eq_u32_e32 vcc, 0, v172
	s_waitcnt lgkmcnt(2)
	v_lshrrev_b32_e32 v108, 7, v170
	v_cndmask_b32_e32 v178, v174, v173, vcc
	v_and_b32_e32 v175, 64, v171
	v_cmp_eq_u32_e32 vcc, 0, v175
	s_waitcnt lgkmcnt(0)
	v_lshrrev_b32_e32 v106, 7, v171
	v_cndmask_b32_e32 v179, v177, v176, vcc
	v_mov_b32_e32 v110, v178
	v_mov_b32_e32 v156, v179
	v_ashrrev_i32_e32 v181, 31, v108
	v_mov_b32_e32 v180, v108
	v_ashrrev_i32_e32 v183, 31, v106
	v_mov_b32_e32 v182, v106
	v_lshl_add_u64 v[180:181], v[180:181], 2, s[6:7]
	v_lshl_add_u64 v[182:183], v[182:183], 2, s[6:7]
	global_load_dword v218, v[180:181], off
	global_load_dword v219, v[182:183], off
	s_mov_b32 s10, 0
	v_mov_b32_e32 v107, 0
	s_waitcnt vmcnt(6)
	v_lshlrev_b32_e32 v88, 16, v32
	v_readlane_b32 s4, v108, 0
	v_readlane_b32 s30, v108, 1
	v_readlane_b32 s34, v108, 2
	v_readlane_b32 s36, v108, 3
	v_readlane_b32 s38, v108, 4
	v_readlane_b32 s40, v108, 5
	v_readlane_b32 s42, v108, 6
	v_readlane_b32 s44, v108, 7
	s_ashr_i32 s5, s4, 31
	s_ashr_i32 s31, s30, 31
	s_ashr_i32 s35, s34, 31
	s_ashr_i32 s37, s36, 31
	s_ashr_i32 s39, s38, 31
	s_ashr_i32 s41, s40, 31
	s_ashr_i32 s43, s42, 31
	s_ashr_i32 s45, s44, 31
	s_lshl_b64 s[4:5], s[4:5], 10
	s_lshl_b64 s[30:31], s[30:31], 10
	s_lshl_b64 s[34:35], s[34:35], 10
	s_lshl_b64 s[36:37], s[36:37], 10
	s_lshl_b64 s[38:39], s[38:39], 10
	s_lshl_b64 s[40:41], s[40:41], 10
	s_lshl_b64 s[42:43], s[42:43], 10
	s_lshl_b64 s[44:45], s[44:45], 10
	v_lshl_add_u64 v[48:49], v[98:99], 0, s[4:5]
	v_lshl_add_u64 v[50:51], v[98:99], 0, s[30:31]
	v_lshl_add_u64 v[52:53], v[98:99], 0, s[34:35]
	v_lshl_add_u64 v[54:55], v[98:99], 0, s[36:37]
	v_lshl_add_u64 v[56:57], v[98:99], 0, s[38:39]
	v_lshl_add_u64 v[58:59], v[98:99], 0, s[40:41]
	v_lshl_add_u64 v[60:61], v[98:99], 0, s[42:43]
	v_lshl_add_u64 v[62:63], v[98:99], 0, s[44:45]
	global_load_dwordx4 v[0:3], v[48:49], off
	global_load_dwordx4 v[4:7], v[50:51], off
	global_load_dwordx4 v[8:11], v[52:53], off
	global_load_dwordx4 v[12:15], v[54:55], off
	global_load_dwordx4 v[16:19], v[56:57], off
	global_load_dwordx4 v[20:23], v[58:59], off
	global_load_dwordx4 v[24:27], v[60:61], off
	global_load_dwordx4 v[28:31], v[62:63], off
	s_waitcnt vmcnt(11)
	v_lshlrev_b32_e32 v64, 16, v44
	v_and_b32_e32 v65, 0xffff0000, v44
	v_lshlrev_b32_e32 v66, 16, v45
	v_and_b32_e32 v67, 0xffff0000, v45
	v_lshlrev_b32_e32 v68, 16, v46
	v_and_b32_e32 v69, 0xffff0000, v46
	v_lshlrev_b32_e32 v70, 16, v47
	v_and_b32_e32 v71, 0xffff0000, v47
	v_lshlrev_b32_e32 v72, 16, v40
	v_and_b32_e32 v73, 0xffff0000, v40
	v_lshlrev_b32_e32 v74, 16, v41
	v_and_b32_e32 v75, 0xffff0000, v41
	v_lshlrev_b32_e32 v76, 16, v42
	v_and_b32_e32 v77, 0xffff0000, v42
	v_lshlrev_b32_e32 v78, 16, v43
	v_and_b32_e32 v79, 0xffff0000, v43
	v_lshlrev_b32_e32 v80, 16, v36
	v_and_b32_e32 v81, 0xffff0000, v36
	v_lshlrev_b32_e32 v82, 16, v37
	v_and_b32_e32 v83, 0xffff0000, v37
	v_lshlrev_b32_e32 v84, 16, v38
	v_and_b32_e32 v85, 0xffff0000, v38
	v_lshlrev_b32_e32 v86, 16, v39
	v_and_b32_e32 v87, 0xffff0000, v39
	v_and_b32_e32 v89, 0xffff0000, v32
	v_lshlrev_b32_e32 v90, 16, v33
	v_and_b32_e32 v91, 0xffff0000, v33
	v_lshlrev_b32_e32 v92, 16, v34
	v_and_b32_e32 v93, 0xffff0000, v34
	v_lshlrev_b32_e32 v94, 16, v35
	v_and_b32_e32 v95, 0xffff0000, v35

; __device__ __forceinline__ float gelu1(float x) { return 0.5f * x * (1.0f + erff(x * 0.70710678118654752f)); }
; __global__ void __launch_bounds__(NT, 2) mk_fwd(Args args) {
;     ...
;                 const float d = dv * SCL[ev];
;                 const float a = gelu1(d) * gv * SCL[16384 + ev];
;                 if (hh) act1 = a; else act0 = a;
.LBB0_891:
	v_ashrrev_i32_e32 v109, 31, v108
	v_lshl_add_u64 v[0:1], v[108:109], 2, s[6:7]
	v_mov_b32_e32 v2, v218
	v_mul_f32_e32 v111, v107, v2
	v_mul_f32_e32 v112, 0x3f3504f3, v111
	v_cmp_nlt_f32_e64 s[4:5], |v112|, 1.0
	s_and_saveexec_b64 s[30:31], s[4:5]
	s_xor_b64 s[4:5], exec, s[30:31]
	s_cbranch_execz .LBB0_893
	v_fma_f32 v2, |v112|, s11, v154
	v_fma_f32 v2, |v112|, v2, s13
	v_fma_f32 v2, |v112|, v2, s15
	v_fma_f32 v2, |v112|, v2, s17
	v_fma_f32 v2, |v112|, v2, s19
	v_fma_f32 v2, |v112|, v2, s21
	v_fma_f32 v2, |v112|, v2, |v112|
	v_mul_f32_e32 v3, 0xbfb8aa3b, v2
	v_fma_f32 v4, v2, s23, -v3
	v_rndne_f32_e32 v5, v3
	v_fmac_f32_e32 v4, 0xb2a5705f, v2
	v_sub_f32_e32 v3, v3, v5
	v_add_f32_e32 v3, v3, v4
	v_cvt_i32_f32_e32 v4, v5
	v_exp_f32_e32 v3, v3
	v_cmp_nlt_f32_e32 vcc, s25, v2
	v_ldexp_f32 v3, v3, v4
	s_nop 0
	v_cndmask_b32_e32 v3, 0, v3, vcc
	v_cmp_ngt_f32_e32 vcc, s26, v2
	s_nop 1
	v_cndmask_b32_e32 v2, v155, v3, vcc
	v_sub_f32_e32 v113, 1.0, v2

; __device__ __forceinline__ float gelu1(float x) { return 0.5f * x * (1.0f + erff(x * 0.70710678118654752f)); }
; __global__ void __launch_bounds__(NT, 2) mk_fwd(Args args) {
;     ...
;                 const float d = dv * SCL[ev];
;                 const float a = gelu1(d) * gv * SCL[16384 + ev];
;                 if (hh) act1 = a; else act0 = a;
.LBB0_900:
	v_ashrrev_i32_e32 v107, 31, v106
	v_lshl_add_u64 v[0:1], v[106:107], 2, s[6:7]
	v_mov_b32_e32 v2, v219
	v_mul_f32_e32 v107, v109, v2
	v_mul_f32_e32 v109, 0x3f3504f3, v107
	v_cmp_nlt_f32_e64 s[4:5], |v109|, 1.0
	s_and_saveexec_b64 s[30:31], s[4:5]
	s_xor_b64 s[4:5], exec, s[30:31]
	s_cbranch_execz .LBB0_902
	v_fma_f32 v2, |v109|, s11, v154
	v_fma_f32 v2, |v109|, v2, s13
	v_fma_f32 v2, |v109|, v2, s15
	v_fma_f32 v2, |v109|, v2, s17
	v_fma_f32 v2, |v109|, v2, s19
	v_fma_f32 v2, |v109|, v2, s21
	v_fma_f32 v2, |v109|, v2, |v109|
	v_mul_f32_e32 v3, 0xbfb8aa3b, v2
	v_fma_f32 v4, v2, s23, -v3
	v_rndne_f32_e32 v5, v3
	v_fmac_f32_e32 v4, 0xb2a5705f, v2
	v_sub_f32_e32 v3, v3, v5
	v_add_f32_e32 v3, v3, v4
	v_cvt_i32_f32_e32 v4, v5
	v_exp_f32_e32 v3, v3
	v_cmp_nlt_f32_e32 vcc, s25, v2
	v_ldexp_f32 v3, v3, v4
	s_nop 0
	v_cndmask_b32_e32 v3, 0, v3, vcc
	v_cmp_ngt_f32_e32 vcc, s26, v2
	s_nop 1
	v_cndmask_b32_e32 v2, v155, v3, vcc
	v_sub_f32_e32 v157, 1.0, v2
